# first grid barrier: 16 XCD-slot polls batched into one round trip; attention: no full drain between Q loads and first K/V loads
# speedup vs baseline: 1.0132x; 1.0083x over previous
; DI unsigned xb_ld(unsigned* p)              { return __hip_atomic_load(p, __ATOMIC_RELAXED, __HIP_MEMORY_SCOPE_AGENT); }
; DI void xcd_barrier_complete(unsigned* bar, unsigned x, unsigned& nloc, unsigned& nx) {
;     const unsigned G = gridDim.x * gridDim.y * gridDim.z;
;     unsigned sum, cnt, mine, sp = 0u;
;     for (;;) {
;         sum = 0u; cnt = 0u; mine = 0u;
; #pragma unroll
;         for (unsigned j = 0; j < 16; ++j) { const unsigned c = xb_ld(&bar[XB_XCNT(j)]); sum += c; cnt += (c > 0u) ? 1u : 0u; mine = (j == x) ? c : mine; }
;         if (sum == G) break;
;         __builtin_amdgcn_s_sleep(1);
;         if ((++sp & 255u) == 0u) { if (xb_ld(&bar[XB_TMO])) break; if (sp > XB_SPIN_CAP) { atomicAdd(&bar[XB_TMO], 1u); break; } }
;     }
;     nloc = mine > 0u ? mine : 1u; nx = cnt > 0u ? cnt : 1u;
; }
.LBB0_132:
	v_readlane_b32 s8, v254, 15
	s_waitcnt lgkmcnt(0)
	v_readlane_b32 s6, v254, 18
	v_readlane_b32 s7, v254, 19
	s_nop 4
	global_load_dword v0, v33, s[6:7] sc1
	v_readlane_b32 s6, v254, 20
	v_readlane_b32 s7, v254, 21
	s_nop 4
	global_load_dword v1, v33, s[6:7] sc1
	v_readlane_b32 s6, v254, 22
	v_readlane_b32 s7, v254, 23
	s_nop 4
	global_load_dword v2, v33, s[6:7] sc1
	v_readlane_b32 s6, v254, 24
	v_readlane_b32 s7, v254, 25
	s_nop 4
	global_load_dword v3, v33, s[6:7] sc1
	v_readlane_b32 s6, v254, 26
	v_readlane_b32 s7, v254, 27
	s_nop 4
	global_load_dword v4, v33, s[6:7] sc1
	v_readlane_b32 s6, v254, 28
	v_readlane_b32 s7, v254, 29
	s_nop 4
	global_load_dword v5, v33, s[6:7] sc1
	v_readlane_b32 s6, v254, 30
	v_readlane_b32 s7, v254, 31
	s_nop 4
	global_load_dword v6, v33, s[6:7] sc1
	v_readlane_b32 s6, v254, 32
	v_readlane_b32 s7, v254, 33
	s_nop 4
	global_load_dword v7, v33, s[6:7] sc1
	v_readlane_b32 s6, v254, 34
	v_readlane_b32 s7, v254, 35
	s_nop 4
	global_load_dword v8, v33, s[6:7] sc1
	v_readlane_b32 s6, v254, 36
	v_readlane_b32 s7, v254, 37
	s_nop 4
	global_load_dword v9, v33, s[6:7] sc1
	v_readlane_b32 s6, v254, 38
	v_readlane_b32 s7, v254, 39
	s_nop 4
	global_load_dword v10, v33, s[6:7] sc1
	v_readlane_b32 s6, v254, 40
	v_readlane_b32 s7, v254, 41
	s_nop 4
	global_load_dword v11, v33, s[6:7] sc1
	v_readlane_b32 s6, v254, 42
	v_readlane_b32 s7, v254, 43
	s_nop 4
	global_load_dword v12, v33, s[6:7] sc1
	v_readlane_b32 s6, v254, 44
	v_readlane_b32 s7, v254, 45
	s_nop 4
	global_load_dword v13, v33, s[6:7] sc1
	v_readlane_b32 s6, v254, 46
	v_readlane_b32 s7, v254, 47
	s_nop 4
	global_load_dword v14, v33, s[6:7] sc1
	v_readlane_b32 s6, v254, 48
	v_readlane_b32 s7, v254, 49
	s_nop 4
	global_load_dword v15, v33, s[6:7] sc1
	s_mov_b64 s[6:7], -1
	s_waitcnt vmcnt(0)
	v_add_u32_e32 v16, v1, v0
	v_add_u32_e32 v16, v16, v2
	v_add_u32_e32 v16, v16, v3
	v_add_u32_e32 v16, v16, v4
	v_add_u32_e32 v16, v16, v5
	v_add_u32_e32 v16, v16, v6
	v_add_u32_e32 v16, v16, v7
	v_add_u32_e32 v16, v16, v8
	v_add_u32_e32 v16, v16, v9
	v_add_u32_e32 v16, v16, v10
	v_add_u32_e32 v16, v16, v11
	v_add_u32_e32 v16, v16, v12
	v_add_u32_e32 v16, v16, v13
	v_add_u32_e32 v16, v16, v14
	v_add_u32_e32 v16, v16, v15
	v_cmp_eq_u32_e32 vcc, s8, v16
	s_mov_b64 s[8:9], -1
	s_cbranch_vccnz .LBB0_131
	s_and_b32 s6, s13, 0xff
	s_cmp_eq_u32 s6, 0
	s_mov_b64 s[6:7], -1
	s_mov_b64 s[10:11], -1
	s_sleep 1
	s_cbranch_scc0 .LBB0_136
	v_readlane_b32 s6, v254, 16
	v_readlane_b32 s7, v254, 17
	s_nop 4
	global_load_dword v16, v33, s[6:7] sc1
	s_waitcnt vmcnt(0)
	v_cmp_eq_u32_e32 vcc, 0, v16
	s_cbranch_vccnz .LBB0_138
	s_mov_b64 s[10:11], 0
	s_mov_b64 s[6:7], -1

; DI int crow(int i, int h) { return (i & 3) + 8 * (i >> 2) + 4 * h; }
; template <int DV, bool MULT>
; DI void attn_pass(const bf16_t* __restrict__ Kg, const bf16_t* __restrict__ VTg, const bf16x8 (&qf)[4], const int q0, f32x16 (&O)[DV / 32], float& m_run, float& l_run, char* lds, const int gw) {
;     ...
;     if (MULT) {
; #pragma unroll
;         for (int i = 0; i < 16; ++i) { const int d = (l31 - crow(i, hh)) & 15; adjF[i] = (d == 0) ? 0.f : -1e30f; adjM[i] = ((d & 3) == 0) ? ((d == 0) ? 1.f : 0.f) : -1e30f; }
;     }
; DI void attn_phase(const Params& p, const int j, char* lds, const int cidx) {
;     ...
;             const int jj = item - 256;
;             const int qt = 7 - (jj >> 6), r = jj & 63, b = r >> 3, h = r & 7;
;             const int q0 = qt * 256;
;             const size_t tokq = (size_t)(b * SEQ + q0 + w * 32 + l31);
;             bf16x8 qf[4];
; #pragma unroll
;             for (int ks = 0; ks < 4; ++ks) qf[ks] = *(const bf16x8*)(PROJ + tokq * ATT_IN + h * 64 + ks * 16 + 8 * hh);
.LBB0_202:
	s_or_b64 exec, exec, s[4:5]
	s_waitcnt lgkmcnt(0)
	s_barrier
	ds_read_b32 v0, v198
	s_movk_i32 s4, 0x2ff
	s_waitcnt lgkmcnt(0)
	s_barrier
	v_cmp_lt_i32_e32 vcc, s4, v0
	v_readfirstlane_b32 s34, v0
	s_mov_b64 s[4:5], -1
	s_cbranch_vccnz .LBB0_199
	s_cmpk_gt_i32 s34, 0xff
	s_cbranch_scc0 .LBB0_288
	s_lshl_b32 s4, s34, 2
	s_bfe_u32 s8, s34, 0x30003
	s_and_b32 s10, s4, 0x7fffff00
	s_sub_i32 s11, 0xb00, s10
	s_lshl_b32 s4, s8, 11
	s_add_i32 s4, s4, s11
	s_and_b32 s9, s34, 7
	v_add_u32_e32 v130, s4, v139
	v_mov_b64_e32 v[0:1], s[86:87]
	v_mad_i64_i32 v[0:1], s[4:5], v130, s77, v[0:1]
	s_lshl_b32 s88, s9, 7
	v_lshl_add_u64 v[0:1], v[0:1], 0, s[88:89]
	v_mov_b32_e32 v145, v33
	v_lshl_add_u64 v[0:1], v[0:1], 0, v[144:145]
	flat_load_dwordx4 v[98:101], v[0:1]
	flat_load_dwordx4 v[102:105], v[0:1] offset:32
	flat_load_dwordx4 v[106:109], v[0:1] offset:64
	flat_load_dwordx4 v[110:113], v[0:1] offset:96
	v_mbcnt_lo_u32_b32 v1, -1, 0
	v_mbcnt_hi_u32_b32 v1, -1, v1
	s_lshl_b32 s35, s9, 6
	v_or_b32_e32 v10, s71, v1
	v_bfe_u32 v11, v1, 5, 1
	v_ashrrev_i32_e32 v0, 1, v10
	v_and_b32_e32 v0, 0xffffffe0, v0
	v_lshlrev_b32_e32 v146, 2, v11
	s_mul_i32 s4, s8, 0xc00000
	v_add_u32_e32 v145, s11, v0
	v_sub_u32_e32 v0, v1, v146
	s_add_u32 s4, s86, s4
	v_and_b32_e32 v0, 15, v0
	s_addc_u32 s5, s87, 0
	v_cmp_eq_u32_e32 vcc, 0, v0
	v_and_b32_e32 v12, 3, v1
	s_add_u32 s6, s4, s88
	v_cndmask_b32_e64 v147, v201, 0, vcc
	v_cndmask_b32_e64 v0, 0, 1.0, vcc
	v_cmp_eq_u32_e32 vcc, 0, v12
	v_or_b32_e32 v149, 1, v146
	s_addc_u32 s7, s5, 0
	s_lshl_b32 s4, s9, 18
	s_lshl_b32 s5, s8, 22
	v_cndmask_b32_e32 v148, v201, v0, vcc
	v_sub_u32_e32 v0, v10, v149
	s_or_b32 s4, s5, s4
	v_and_b32_e32 v2, 15, v0
	s_add_u32 s20, s30, s4
	v_cmp_eq_u32_e64 s[4:5], 0, v2
	v_and_b32_e32 v0, 3, v0
	v_or_b32_e32 v152, 2, v146
	v_cndmask_b32_e64 v150, v201, 0, s[4:5]
	v_cndmask_b32_e64 v2, 0, 1.0, s[4:5]
	v_cmp_eq_u32_e64 s[4:5], 0, v0
	v_sub_u32_e32 v0, v10, v152
	v_or_b32_e32 v155, 3, v146
	v_cndmask_b32_e64 v151, v201, v2, s[4:5]
	v_and_b32_e32 v2, 15, v0
	v_cmp_eq_u32_e64 s[4:5], 0, v2
	v_and_b32_e32 v0, 3, v0
	v_or_b32_e32 v158, 8, v146
	v_cndmask_b32_e64 v153, v201, 0, s[4:5]
	v_cndmask_b32_e64 v2, 0, 1.0, s[4:5]
	v_cmp_eq_u32_e64 s[4:5], 0, v0
	v_sub_u32_e32 v0, v10, v155
	v_or_b32_e32 v164, 9, v146
	v_cndmask_b32_e64 v154, v201, v2, s[4:5]
	v_and_b32_e32 v2, 15, v0
	v_cmp_eq_u32_e64 s[4:5], 0, v2
	v_and_b32_e32 v0, 3, v0
	v_or_b32_e32 v167, 10, v146
	v_cndmask_b32_e64 v156, v201, 0, s[4:5]
	v_cndmask_b32_e64 v2, 0, 1.0, s[4:5]
	v_cmp_eq_u32_e64 s[4:5], 0, v0
	v_sub_u32_e32 v0, v1, v158
	v_and_b32_e32 v0, 15, v0
	v_cndmask_b32_e64 v157, v201, v2, s[4:5]
	v_cmp_eq_u32_e64 s[4:5], 0, v0
	v_or_b32_e32 v170, 11, v146
	v_or_b32_e32 v174, 17, v146
	v_cndmask_b32_e64 v0, 0, 1.0, s[4:5]
	v_cndmask_b32_e32 v163, v201, v0, vcc
	v_sub_u32_e32 v0, v10, v164
	v_and_b32_e32 v2, 15, v0
	v_cndmask_b32_e64 v159, v201, 0, s[4:5]
	v_cmp_eq_u32_e64 s[4:5], 0, v2
	v_and_b32_e32 v0, 3, v0
	v_or_b32_e32 v177, 18, v146
	v_cndmask_b32_e64 v165, v201, 0, s[4:5]
	v_cndmask_b32_e64 v2, 0, 1.0, s[4:5]
	v_cmp_eq_u32_e64 s[4:5], 0, v0
	v_sub_u32_e32 v0, v10, v167
	v_or_b32_e32 v180, 19, v146
	v_cndmask_b32_e64 v166, v201, v2, s[4:5]
	v_and_b32_e32 v2, 15, v0
	v_cmp_eq_u32_e64 s[4:5], 0, v2
	v_and_b32_e32 v0, 3, v0
	v_lshlrev_b32_e32 v13, 3, v1
	v_cndmask_b32_e64 v168, v201, 0, s[4:5]
	v_cndmask_b32_e64 v2, 0, 1.0, s[4:5]
	v_cmp_eq_u32_e64 s[4:5], 0, v0
	v_sub_u32_e32 v0, v10, v170
	v_add_u32_e32 v4, 0x200, v10
	v_cndmask_b32_e64 v169, v201, v2, s[4:5]
	v_and_b32_e32 v2, 15, v0
	v_cmp_eq_u32_e64 s[4:5], 0, v2
	v_and_b32_e32 v0, 3, v0
	v_ashrrev_i32_e32 v185, 3, v4
	v_cndmask_b32_e64 v171, v201, 0, s[4:5]
	v_cndmask_b32_e64 v2, 0, 1.0, s[4:5]
	v_cmp_eq_u32_e64 s[4:5], 0, v0
	v_sub_u32_e32 v0, v10, v174
	v_ashrrev_i32_e32 v4, 4, v4
	v_cndmask_b32_e64 v172, v201, v2, s[4:5]
	v_and_b32_e32 v2, 15, v0
	v_cmp_eq_u32_e64 s[4:5], 0, v2
	v_and_b32_e32 v0, 3, v0
	s_addc_u32 s21, s31, 0
	v_cndmask_b32_e64 v175, v201, 0, s[4:5]
	v_cndmask_b32_e64 v2, 0, 1.0, s[4:5]
	v_cmp_eq_u32_e64 s[4:5], 0, v0
; template <int DV, bool MULT>
; DI void attn_pass(const bf16_t* __restrict__ Kg, const bf16_t* __restrict__ VTg, const bf16x8 (&qf)[4], const int q0, f32x16 (&O)[DV / 32], float& m_run, float& l_run, char* lds, const int gw) {
;     ...
;     u32x4 rk[2], rv[NV];
; #pragma unroll
;     for (int i = 0; i < 2; ++i) { const int c = tid + 512 * i, key = c >> 3, d8 = c & 7; rk[i] = *(const u32x4*)(Kg + (size_t)key * ATT_IN + d8 * 8); }
; #pragma unroll
;     for (int i = 0; i < NV; ++i) { const int c = tid + 512 * i, dv = c >> 4, k8 = c & 15; rv[i] = *(const u32x4*)(VTg + (size_t)dv * SEQ + k8 * 8); }
; DI void attn_phase(const Params& p, const int j, char* lds, const int cidx) {
;     ...
;             f32x16 O[2];
; #pragma unroll
;             for (int dt = 0; dt < 2; ++dt)
; #pragma unroll
;                 for (int i = 0; i < 16; ++i) O[dt][i] = 0.f;
;             float m_run = -1e29f, l_run = 0.f;
	v_sub_u32_e32 v0, v10, v177
	v_lshlrev_b32_e32 v14, 4, v1
	v_cndmask_b32_e64 v176, v201, v2, s[4:5]
	v_and_b32_e32 v2, 15, v0
	v_cmp_eq_u32_e64 s[4:5], 0, v2
	v_and_b32_e32 v0, 3, v0
	v_ashrrev_i32_e32 v5, 31, v4
	v_cndmask_b32_e64 v178, v201, 0, s[4:5]
	v_cndmask_b32_e64 v2, 0, 1.0, s[4:5]
	v_cmp_eq_u32_e64 s[4:5], 0, v0
	v_sub_u32_e32 v0, v10, v180
	v_mov_b32_e32 v7, v33
	v_cndmask_b32_e64 v179, v201, v2, s[4:5]
	v_and_b32_e32 v2, 15, v0
	v_cmp_eq_u32_e64 s[4:5], 0, v2
	v_and_b32_e32 v0, 3, v0
	v_and_b32_e32 v32, 0x70, v14
	v_cndmask_b32_e64 v181, v201, 0, s[4:5]
	v_cndmask_b32_e64 v2, 0, 1.0, s[4:5]
	v_cmp_eq_u32_e64 s[4:5], 0, v0
	v_and_b32_e32 v0, 0x78, v13
	v_lshlrev_b32_e32 v6, 1, v0
	v_cndmask_b32_e64 v182, v201, v2, s[4:5]
	v_ashrrev_i32_e32 v2, 4, v10
	v_ashrrev_i32_e32 v3, 31, v2
	v_lshlrev_b64 v[134:135], 12, v[2:3]
	v_lshlrev_b64 v[136:137], 12, v[4:5]
	v_lshl_add_u64 v[6:7], s[20:21], 0, v[6:7]
	v_lshl_add_u64 v[132:133], s[6:7], 0, v[32:33]
	v_lshl_add_u64 v[8:9], v[6:7], 0, v[136:137]
	v_lshl_add_u64 v[6:7], v[6:7], 0, v[134:135]
	v_ashrrev_i32_e32 v184, 3, v10
	flat_load_dwordx4 v[122:125], v[8:9]
	flat_load_dwordx4 v[126:129], v[6:7]
	v_mad_i64_i32 v[6:7], s[4:5], v185, s77, v[132:133]
	v_mad_i64_i32 v[8:9], s[4:5], v184, s77, v[132:133]
	flat_load_dwordx4 v[114:117], v[6:7] offset:1024
	flat_load_dwordx4 v[118:121], v[8:9] offset:1024
	v_or_b32_e32 v183, 24, v146
	v_sub_u32_e32 v3, v1, v183
	v_and_b32_e32 v3, 15, v3
	v_cmp_eq_u32_e64 s[4:5], 0, v3
	v_or_b32_e32 v188, 25, v146
	v_or_b32_e32 v191, 26, v146
	v_cndmask_b32_e64 v3, 0, 1.0, s[4:5]
	v_cndmask_b32_e32 v187, v201, v3, vcc
	v_sub_u32_e32 v3, v10, v188
	v_and_b32_e32 v5, 15, v3
	v_cmp_eq_u32_e32 vcc, 0, v5
	v_and_b32_e32 v3, 3, v3
	v_or_b32_e32 v195, 27, v146
	v_cndmask_b32_e64 v189, v201, 0, vcc
	v_cndmask_b32_e64 v5, 0, 1.0, vcc
	v_cmp_eq_u32_e32 vcc, 0, v3
	v_sub_u32_e32 v3, v10, v191
	v_cndmask_b32_e64 v186, v201, 0, s[4:5]
	v_cndmask_b32_e32 v190, v201, v5, vcc
	v_and_b32_e32 v5, 15, v3
	v_cmp_eq_u32_e32 vcc, 0, v5
	v_and_b32_e32 v3, 3, v3
	s_movk_i32 s4, 0x90
	v_cndmask_b32_e64 v192, v201, 0, vcc
	v_cndmask_b32_e64 v5, 0, 1.0, vcc
	v_cmp_eq_u32_e32 vcc, 0, v3
	v_sub_u32_e32 v3, v10, v195
	v_and_b32_e32 v6, 0xe0, v14
	v_cndmask_b32_e32 v194, v201, v5, vcc
	v_and_b32_e32 v5, 15, v3
	v_cmp_eq_u32_e32 vcc, 0, v5
	v_and_b32_e32 v3, 3, v3
	v_mul_lo_u32 v7, v185, s4
	v_cndmask_b32_e64 v200, v201, 0, vcc
	v_cndmask_b32_e64 v5, 0, 1.0, vcc
	v_cmp_eq_u32_e32 vcc, 0, v3
	s_movk_i32 s6, 0x110
	v_and_b32_e32 v8, 8, v13
	v_cndmask_b32_e32 v204, v201, v5, vcc
	v_mul_lo_u32 v5, v184, s4
	v_mad_u64_u32 v[2:3], s[4:5], v2, s6, v[6:7]
	v_or_b32_e32 v9, v2, v8
	v_mad_u64_u32 v[2:3], s[4:5], v4, s6, v[6:7]
	v_mov_b32_e32 v48, v33
	v_mov_b32_e32 v49, v33
	s_sub_i32 s8, 0xc00, s10
	v_and_b32_e32 v1, 31, v1
	v_or_b32_e32 v2, v2, v8
	v_mov_b32_e32 v34, v33
	v_mov_b32_e32 v35, v33
	v_mov_b32_e32 v36, v33
	v_mov_b32_e32 v37, v33
	v_mov_b32_e32 v38, v33
	v_mov_b32_e32 v39, v33
	v_mov_b32_e32 v40, v33
	v_mov_b32_e32 v41, v33
	v_mov_b32_e32 v42, v33
	v_mov_b32_e32 v43, v33
	v_mov_b32_e32 v44, v33
	v_mov_b32_e32 v45, v33
	v_mov_b32_e32 v46, v33
	v_mov_b32_e32 v47, v33
	v_mov_b64_e32 v[64:65], v[48:49]
	v_ashrrev_i32_e32 v131, 31, v130
	s_mov_b32 s36, 0
	v_or_b32_e32 v173, 16, v146
	s_lshr_b32 s37, s8, 7
	v_or_b32_e32 v205, 31, v145
	v_lshlrev_b32_e32 v206, 4, v11
	v_subrev_u32_e32 v207, 63, v145
	v_or_b32_e32 v208, v145, v1
	v_mul_u32_u24_e32 v210, 0x90, v1
	v_cmp_eq_u16_e64 s[4:5], 0, v12
	v_cmp_eq_u16_e64 s[6:7], 1, v12
	v_cmp_eq_u16_e64 s[8:9], 2, v12
	v_cmp_eq_u16_e64 s[10:11], 3, v12
	v_mul_u32_u24_e32 v211, 0x110, v1
	v_mov_b32_e32 v209, 0
	v_mov_b32_e32 v216, 0xefa18f08
	v_add_u32_e32 v212, v32, v5
	v_add_u32_e32 v213, v32, v7
	v_lshlrev_b32_e32 v32, 1, v0
	v_add_u32_e32 v214, 0x4800, v9
	v_add_u32_e32 v215, 0x4800, v2
	v_mov_b64_e32 v[62:63], v[46:47]
	v_mov_b64_e32 v[60:61], v[44:45]
	v_mov_b64_e32 v[58:59], v[42:43]
	v_mov_b64_e32 v[56:57], v[40:41]
	v_mov_b64_e32 v[54:55], v[38:39]
	v_mov_b64_e32 v[52:53], v[36:37]
	v_mov_b64_e32 v[50:51], v[34:35]
	s_branch .LBB0_206

; template <int DV, bool MULT>
; DI void attn_pass(const bf16_t* __restrict__ Kg, const bf16_t* __restrict__ VTg, const bf16x8 (&qf)[4], const int q0, f32x16 (&O)[DV / 32], float& m_run, float& l_run, char* lds, const int gw) {
;     ...
;     u32x4 rk[2], rv[NV];
; #pragma unroll
;     for (int i = 0; i < 2; ++i) { const int c = tid + 512 * i, key = c >> 3, d8 = c & 7; rk[i] = *(const u32x4*)(Kg + (size_t)key * ATT_IN + d8 * 8); }
; #pragma unroll
;     for (int i = 0; i < NV; ++i) { const int c = tid + 512 * i, dv = c >> 4, k8 = c & 15; rv[i] = *(const u32x4*)(VTg + (size_t)dv * SEQ + k8 * 8); }
; DI void attn_phase(const Params& p, const int j, char* lds, const int cidx) {
;     ...
;             unsigned* O0s = (unsigned*)(lds + 53248) + tid;
; #pragma unroll
;             for (int sub = 0; sub < 2; ++sub) {
;                 bf16x8 qf[4];
; #pragma unroll
;                 for (int ks = 0; ks < 4; ++ks) qf[ks] = *(const bf16x8*)(PROJ + tokq * ATT_IN + 1536 + (2 * h + sub) * 64 + ks * 16 + 8 * hh);
;                 f32x16 O[4];
; #pragma unroll
;                 for (int dt = 0; dt < 4; ++dt)
; #pragma unroll
;                     for (int i = 0; i < 16; ++i) O[dt][i] = 0.f;
;                 float m_run = -1e29f, l_run = 0.f;
;                 attn_pass<128, false>(PROJ + (size_t)(b * SEQ) * ATT_IN + 2048 + (2 * h + sub) * 64, VT + (size_t)(b * 1024 + 512 + h * 128) * SEQ, qf, q0, O, m_run, l_run, lds, p.wave);
.LBB0_288:
	s_and_b64 vcc, exec, s[4:5]
	s_cbranch_vccz .LBB0_198
	s_lshl_b32 s4, s34, 3
	s_bfe_u32 s8, s34, 0x30002
	s_and_b32 s10, s4, 0xffffff00
	s_sub_i32 s21, 0x700, s10
	s_lshl_b32 s4, s8, 11
	s_add_i32 s4, s4, s21
	v_add_u32_e32 v146, s4, v139
	s_and_b32 s9, s34, 3
	v_mad_i64_i32 v[0:1], s[4:5], v146, s77, v[142:143]
	s_lshl_b32 s22, s9, 7
	s_mul_i32 s4, s8, 0xc00000
	s_add_u32 s4, s86, s4
	s_addc_u32 s5, s87, 0
	s_add_u32 s6, s4, 0x1000
	s_addc_u32 s7, s5, 0
	s_lshl_b32 s4, s9, 19
	s_lshl_b32 s5, s8, 22
	s_or_b32 s4, s5, s4
	s_add_u32 s4, s30, s4
	s_addc_u32 s5, s31, 0
	s_add_u32 s4, s4, 0x200000
	s_addc_u32 s5, s5, 0
	s_lshl_b32 s88, s9, 8
	v_lshl_add_u64 v[148:149], v[0:1], 0, s[88:89]
	flat_load_dwordx4 v[98:101], v[148:149] offset:3072
	flat_load_dwordx4 v[102:105], v[148:149] offset:3104
	flat_load_dwordx4 v[106:109], v[148:149] offset:3136
	flat_load_dwordx4 v[110:113], v[148:149] offset:3168
	v_mbcnt_lo_u32_b32 v14, -1, 0
	v_mbcnt_hi_u32_b32 v14, -1, v14
	s_sub_i32 s8, 0x800, s10
	v_or_b32_e32 v15, s71, v14
	v_ashrrev_i32_e32 v0, 4, v15
	v_ashrrev_i32_e32 v1, 31, v0
	v_lshlrev_b64 v[152:153], 12, v[0:1]
	v_add_u32_e32 v1, 0x400, v15
	v_lshlrev_b32_e32 v17, 3, v14
	v_ashrrev_i32_e32 v4, 4, v1
	v_add_u32_e32 v1, 0x600, v15
	v_add_u32_e32 v2, 0x200, v15
	v_and_b32_e32 v16, 0x78, v17
	v_ashrrev_i32_e32 v6, 4, v1
	s_lshr_b32 s20, s8, 7
	v_ashrrev_i32_e32 v163, 3, v2
	v_ashrrev_i32_e32 v2, 4, v2
	v_ashrrev_i32_e32 v7, 31, v6
	v_lshlrev_b32_e32 v8, 1, v16
	v_mov_b32_e32 v9, v33
	s_add_u32 s8, s6, s88
	v_lshlrev_b32_e32 v18, 4, v14
	v_ashrrev_i32_e32 v3, 31, v2
	v_ashrrev_i32_e32 v5, 31, v4
	v_lshlrev_b64 v[158:159], 12, v[6:7]
	v_lshl_add_u64 v[8:9], s[4:5], 0, v[8:9]
	s_addc_u32 s9, s7, 0
	v_and_b32_e32 v32, 0x70, v18
	v_lshlrev_b64 v[154:155], 12, v[2:3]
	v_lshlrev_b64 v[156:157], 12, v[4:5]
	v_lshl_add_u64 v[10:11], v[8:9], 0, v[158:159]
	v_lshl_add_u64 v[150:151], s[8:9], 0, v[32:33]
	v_lshl_add_u64 v[12:13], v[8:9], 0, v[156:157]
	flat_load_dwordx4 v[130:133], v[10:11]
	flat_load_dwordx4 v[134:137], v[12:13]
	v_lshl_add_u64 v[10:11], v[8:9], 0, v[154:155]
	v_lshl_add_u64 v[8:9], v[8:9], 0, v[152:153]
	v_ashrrev_i32_e32 v145, 3, v15
	flat_load_dwordx4 v[122:125], v[10:11]
	flat_load_dwordx4 v[126:129], v[8:9]
	v_mad_i64_i32 v[8:9], s[8:9], v163, s77, v[150:151]
	v_mad_i64_i32 v[10:11], s[8:9], v145, s77, v[150:151]
	flat_load_dwordx4 v[114:117], v[8:9]
	flat_load_dwordx4 v[118:121], v[10:11]
	v_ashrrev_i32_e32 v1, 1, v15
	v_and_b32_e32 v1, 0xffffffe0, v1
	v_add_u32_e32 v164, s21, v1
	v_bfe_u32 v1, v14, 5, 1
	v_and_b32_e32 v8, 0xe0, v18
	s_movk_i32 s8, 0x90
	s_movk_i32 s10, 0x110
	v_lshlrev_b32_e32 v167, 4, v1
	v_lshlrev_b32_e32 v168, 2, v1
	v_mul_lo_u32 v18, v145, s8
	v_mul_lo_u32 v19, v163, s8
	v_mad_u64_u32 v[0:1], s[8:9], v0, s10, v[8:9]
	v_and_b32_e32 v5, 8, v17
	v_or_b32_e32 v17, v0, v5
	v_mad_u64_u32 v[0:1], s[8:9], v2, s10, v[8:9]
	v_or_b32_e32 v20, v0, v5
	v_mad_u64_u32 v[0:1], s[8:9], v4, s10, v[8:9]
	v_or_b32_e32 v21, v0, v5
	v_mad_u64_u32 v[0:1], s[8:9], v6, s10, v[8:9]
	v_and_b32_e32 v3, 31, v14
	v_or_b32_e32 v22, v0, v5
	v_mov_b32_e32 v14, v33
	v_mov_b32_e32 v15, v33
	v_or_b32_e32 v165, v164, v3
	v_mul_u32_u24_e32 v169, 0x90, v3
	v_mul_u32_u24_e32 v170, 0x110, v3
	v_mov_b32_e32 v0, v33
	v_mov_b32_e32 v1, v33
	v_mov_b32_e32 v2, v33
	v_mov_b32_e32 v3, v33
	v_mov_b32_e32 v4, v33
	v_mov_b32_e32 v5, v33
	v_mov_b32_e32 v6, v33
	v_mov_b32_e32 v7, v33
	v_mov_b32_e32 v8, v33
	v_mov_b32_e32 v9, v33
	v_mov_b32_e32 v10, v33
	v_mov_b32_e32 v11, v33
	v_mov_b32_e32 v12, v33
	v_mov_b32_e32 v13, v33
	v_add_u32_e32 v172, v32, v18
	v_add_u32_e32 v173, v32, v19
	v_lshlrev_b32_e32 v32, 1, v16
	v_add_u32_e32 v174, 0x4800, v17
	v_add_u32_e32 v175, 0x4800, v20
	v_add_u32_e32 v176, 0x4800, v21
	v_add_u32_e32 v177, 0x4800, v22
	v_mov_b64_e32 v[30:31], v[14:15]
	v_mov_b64_e32 v[48:49], v[14:15]
	v_mov_b64_e32 v[64:65], v[14:15]
	v_ashrrev_i32_e32 v147, 31, v146
	v_or_b32_e32 v166, 31, v164
	s_mov_b32 s23, 0
	v_mov_b32_e32 v171, 0
	v_mov_b32_e32 v178, 0xefa18f08
	v_mov_b64_e32 v[28:29], v[12:13]
	v_mov_b64_e32 v[26:27], v[10:11]
	v_mov_b64_e32 v[24:25], v[8:9]
	v_mov_b64_e32 v[22:23], v[6:7]
	v_mov_b64_e32 v[20:21], v[4:5]
	v_mov_b64_e32 v[18:19], v[2:3]
	v_mov_b64_e32 v[16:17], v[0:1]
	v_mov_b64_e32 v[46:47], v[12:13]
	v_mov_b64_e32 v[44:45], v[10:11]
	v_mov_b64_e32 v[42:43], v[8:9]
	v_mov_b64_e32 v[40:41], v[6:7]
	v_mov_b64_e32 v[38:39], v[4:5]
	v_mov_b64_e32 v[36:37], v[2:3]
	v_mov_b64_e32 v[34:35], v[0:1]
	v_mov_b64_e32 v[62:63], v[12:13]
	v_mov_b64_e32 v[60:61], v[10:11]
	v_mov_b64_e32 v[58:59], v[8:9]
	v_mov_b64_e32 v[56:57], v[6:7]
	v_mov_b64_e32 v[54:55], v[4:5]
	v_mov_b64_e32 v[52:53], v[2:3]
	v_mov_b64_e32 v[50:51], v[0:1]
	s_branch .LBB0_291

; DI unsigned pk_bf16(float a, float b) { f32x2_t v = {a, b}; bf16x2_t r = __builtin_convertvector(v, bf16x2_t); return __builtin_bit_cast(unsigned, r); }
; DI float shx(float v, int mask) { const int l = olane(); return __builtin_bit_cast(float, __builtin_amdgcn_ds_bpermute(((l ^ mask) & 63) << 2, __builtin_bit_cast(int, v))); }
; DI void attn_phase(const Params& p, const int j, char* lds, const int cidx) {
;     ...
;                 const float lt = l_run + shx(l_run, 32);
;                 const float inv = 1.f / lt;
;                 if (sub == 0) {
; #pragma unroll
;                     for (int dt = 0; dt < 4; ++dt)
; #pragma unroll
;                         for (int i = 0; i < 8; ++i) O0s[(dt * 8 + i) * 512] = pk_bf16(O[dt][2 * i] * inv, O[dt][2 * i + 1] * inv);
.LBB0_304:
	v_mbcnt_lo_u32_b32 v32, -1, 0
	v_mbcnt_hi_u32_b32 v32, -1, v32
	v_mov_b32_e32 v167, 0
	v_lshlrev_b32_e32 v32, 2, v32
	v_bitop3_b32 v32, v32, s78, v199 bitop3:0x6c
	ds_bpermute_b32 v32, v32, v171
	v_mov_b32_e32 v176, 0xefa18f08
	s_waitcnt lgkmcnt(0)
	v_add_f32_e32 v32, v171, v32
	v_div_scale_f32 v66, s[8:9], v32, v32, 1.0
	v_rcp_f32_e32 v67, v66
	v_div_scale_f32 v68, vcc, 1.0, v32, 1.0
	s_lshl_b32 s8, s22, 1
	v_fma_f32 v69, -v66, v67, 1.0
	v_fmac_f32_e32 v67, v69, v67
	v_mul_f32_e32 v69, v68, v67
	v_fma_f32 v70, -v66, v69, v68
	v_fmac_f32_e32 v69, v70, v67
	v_fma_f32 v66, -v66, v69, v68
	v_div_fmas_f32 v66, v66, v67, v69
	v_div_fixup_f32 v32, v66, v32, 1.0
	v_pk_mul_f32 v[50:51], v[50:51], v[32:33] op_sel_hi:[1,0]
	v_pk_mul_f32 v[52:53], v[52:53], v[32:33] op_sel_hi:[1,0]
	v_cvt_pk_bf16_f32 v50, v50, v51
	v_cvt_pk_bf16_f32 v51, v52, v53
	v_pk_mul_f32 v[54:55], v[54:55], v[32:33] op_sel_hi:[1,0]
	ds_write2st64_b32 v160, v50, v51 offset0:208 offset1:216
	v_pk_mul_f32 v[50:51], v[56:57], v[32:33] op_sel_hi:[1,0]
	v_cvt_pk_bf16_f32 v52, v54, v55
	v_cvt_pk_bf16_f32 v50, v50, v51
	ds_write2st64_b32 v160, v52, v50 offset0:224 offset1:232
	v_pk_mul_f32 v[50:51], v[58:59], v[32:33] op_sel_hi:[1,0]
	v_pk_mul_f32 v[34:35], v[34:35], v[32:33] op_sel_hi:[1,0]
	v_cvt_pk_bf16_f32 v52, v50, v51
	v_pk_mul_f32 v[50:51], v[60:61], v[32:33] op_sel_hi:[1,0]
	v_pk_mul_f32 v[16:17], v[16:17], v[32:33] op_sel_hi:[1,0]
	v_cvt_pk_bf16_f32 v50, v50, v51
	ds_write2st64_b32 v160, v52, v50 offset0:240 offset1:248
	v_pk_mul_f32 v[50:51], v[62:63], v[32:33] op_sel_hi:[1,0]
	v_pk_mul_f32 v[0:1], v[0:1], v[32:33] op_sel_hi:[1,0]
	v_cvt_pk_bf16_f32 v52, v50, v51
	v_pk_mul_f32 v[50:51], v[64:65], v[32:33] op_sel_hi:[1,0]
	s_or_b32 s88, s8, 0x80
	v_cvt_pk_bf16_f32 v50, v50, v51
	ds_write2st64_b32 v161, v52, v50 offset0:48 offset1:56
	v_cvt_pk_bf16_f32 v50, v34, v35
	v_pk_mul_f32 v[34:35], v[36:37], v[32:33] op_sel_hi:[1,0]
	s_movk_i32 s9, 0x110
	v_cvt_pk_bf16_f32 v34, v34, v35
	ds_write2st64_b32 v161, v50, v34 offset0:64 offset1:72
	v_pk_mul_f32 v[34:35], v[38:39], v[32:33] op_sel_hi:[1,0]
	s_nop 0
	v_cvt_pk_bf16_f32 v36, v34, v35
	v_pk_mul_f32 v[34:35], v[40:41], v[32:33] op_sel_hi:[1,0]
	s_nop 0
	v_cvt_pk_bf16_f32 v34, v34, v35
	ds_write2st64_b32 v161, v36, v34 offset0:80 offset1:88
	v_pk_mul_f32 v[34:35], v[42:43], v[32:33] op_sel_hi:[1,0]
	s_nop 0
	v_cvt_pk_bf16_f32 v36, v34, v35
	v_pk_mul_f32 v[34:35], v[44:45], v[32:33] op_sel_hi:[1,0]
	s_nop 0
	v_cvt_pk_bf16_f32 v34, v34, v35
	ds_write2st64_b32 v161, v36, v34 offset0:96 offset1:104
	v_pk_mul_f32 v[34:35], v[46:47], v[32:33] op_sel_hi:[1,0]
	s_nop 0
	v_cvt_pk_bf16_f32 v36, v34, v35
	v_pk_mul_f32 v[34:35], v[48:49], v[32:33] op_sel_hi:[1,0]
	s_nop 0
	v_cvt_pk_bf16_f32 v34, v34, v35
	ds_write2st64_b32 v161, v36, v34 offset0:112 offset1:120
	v_cvt_pk_bf16_f32 v34, v16, v17
	v_pk_mul_f32 v[16:17], v[18:19], v[32:33] op_sel_hi:[1,0]
	s_nop 0
	v_cvt_pk_bf16_f32 v16, v16, v17
	ds_write2st64_b32 v161, v34, v16 offset0:128 offset1:136
	v_pk_mul_f32 v[16:17], v[20:21], v[32:33] op_sel_hi:[1,0]
	s_nop 0
	v_cvt_pk_bf16_f32 v18, v16, v17
	v_pk_mul_f32 v[16:17], v[22:23], v[32:33] op_sel_hi:[1,0]
	s_nop 0
	v_cvt_pk_bf16_f32 v16, v16, v17
	ds_write2st64_b32 v161, v18, v16 offset0:144 offset1:152
	v_pk_mul_f32 v[16:17], v[24:25], v[32:33] op_sel_hi:[1,0]
	s_nop 0
	v_cvt_pk_bf16_f32 v18, v16, v17
	v_pk_mul_f32 v[16:17], v[26:27], v[32:33] op_sel_hi:[1,0]
	s_nop 0
	v_cvt_pk_bf16_f32 v16, v16, v17
	ds_write2st64_b32 v161, v18, v16 offset0:160 offset1:168
	v_pk_mul_f32 v[16:17], v[28:29], v[32:33] op_sel_hi:[1,0]
	s_nop 0
	v_cvt_pk_bf16_f32 v18, v16, v17
	v_pk_mul_f32 v[16:17], v[30:31], v[32:33] op_sel_hi:[1,0]
	s_nop 0
	v_cvt_pk_bf16_f32 v16, v16, v17
	ds_write2st64_b32 v161, v18, v16 offset0:176 offset1:184
	v_cvt_pk_bf16_f32 v16, v0, v1
	v_pk_mul_f32 v[0:1], v[2:3], v[32:33] op_sel_hi:[1,0]
	s_nop 0
	v_cvt_pk_bf16_f32 v0, v0, v1
	ds_write2st64_b32 v161, v16, v0 offset0:192 offset1:200
	v_pk_mul_f32 v[0:1], v[4:5], v[32:33] op_sel_hi:[1,0]
	s_nop 0
	v_cvt_pk_bf16_f32 v2, v0, v1
	v_pk_mul_f32 v[0:1], v[6:7], v[32:33] op_sel_hi:[1,0]
	s_nop 0
	v_cvt_pk_bf16_f32 v0, v0, v1
	ds_write2st64_b32 v161, v2, v0 offset0:208 offset1:216
	v_pk_mul_f32 v[0:1], v[8:9], v[32:33] op_sel_hi:[1,0]
	s_nop 0
	v_cvt_pk_bf16_f32 v2, v0, v1
	v_pk_mul_f32 v[0:1], v[10:11], v[32:33] op_sel_hi:[1,0]
; template <int DV, bool MULT>
; DI void attn_pass(const bf16_t* __restrict__ Kg, const bf16_t* __restrict__ VTg, const bf16x8 (&qf)[4], const int q0, f32x16 (&O)[DV / 32], float& m_run, float& l_run, char* lds, const int gw) {
;     ...
;     u32x4 rk[2], rv[NV];
; #pragma unroll
;     for (int i = 0; i < 2; ++i) { const int c = tid + 512 * i, key = c >> 3, d8 = c & 7; rk[i] = *(const u32x4*)(Kg + (size_t)key * ATT_IN + d8 * 8); }
; #pragma unroll
;     for (int i = 0; i < NV; ++i) { const int c = tid + 512 * i, dv = c >> 4, k8 = c & 15; rv[i] = *(const u32x4*)(VTg + (size_t)dv * SEQ + k8 * 8); }
; DI void attn_phase(const Params& p, const int j, char* lds, const int cidx) {
;     ...
;                 for (int ks = 0; ks < 4; ++ks) qf[ks] = *(const bf16x8*)(PROJ + tokq * ATT_IN + 1536 + (2 * h + sub) * 64 + ks * 16 + 8 * hh);
;                 f32x16 O[4];
; #pragma unroll
;                 for (int dt = 0; dt < 4; ++dt)
; #pragma unroll
;                     for (int i = 0; i < 16; ++i) O[dt][i] = 0.f;
;                 float m_run = -1e29f, l_run = 0.f;
;                 attn_pass<128, false>(PROJ + (size_t)(b * SEQ) * ATT_IN + 2048 + (2 * h + sub) * 64, VT + (size_t)(b * 1024 + 512 + h * 128) * SEQ, qf, q0, O, m_run, l_run, lds, p.wave);
	v_mov_b32_e32 v11, v33
	v_cvt_pk_bf16_f32 v0, v0, v1
	ds_write2st64_b32 v161, v2, v0 offset0:224 offset1:232
	v_pk_mul_f32 v[0:1], v[12:13], v[32:33] op_sel_hi:[1,0]
	s_nop 0
	v_cvt_pk_bf16_f32 v2, v0, v1
	v_pk_mul_f32 v[0:1], v[14:15], v[32:33] op_sel_hi:[1,0]
	s_nop 0
	v_cvt_pk_bf16_f32 v0, v0, v1
	ds_write2st64_b32 v161, v2, v0 offset0:240 offset1:248
	flat_load_dwordx4 v[98:101], v[148:149] offset:3200
	flat_load_dwordx4 v[102:105], v[148:149] offset:3232
	flat_load_dwordx4 v[106:109], v[148:149] offset:3264
	flat_load_dwordx4 v[110:113], v[148:149] offset:3296
	v_mbcnt_lo_u32_b32 v17, -1, 0
	v_mbcnt_hi_u32_b32 v17, -1, v17
	s_nop 0
	v_or_b32_e32 v18, s71, v17
	v_ashrrev_i32_e32 v2, 4, v18
	v_ashrrev_i32_e32 v3, 31, v2
	v_lshlrev_b64 v[148:149], 12, v[2:3]
	v_add_u32_e32 v3, 0x400, v18
	v_lshlrev_b32_e32 v19, 3, v17
	v_ashrrev_i32_e32 v6, 4, v3
	v_add_u32_e32 v3, 0x600, v18
	v_add_u32_e32 v4, 0x200, v18
	v_and_b32_e32 v16, 0x78, v19
	v_ashrrev_i32_e32 v8, 4, v3
	v_ashrrev_i32_e32 v158, 3, v4
	v_ashrrev_i32_e32 v4, 4, v4
	v_ashrrev_i32_e32 v9, 31, v8
	v_lshlrev_b32_e32 v10, 1, v16
	v_lshlrev_b32_e32 v20, 4, v17
	v_ashrrev_i32_e32 v5, 31, v4
	v_ashrrev_i32_e32 v7, 31, v6
	v_lshlrev_b64 v[154:155], 12, v[8:9]
	v_lshl_add_u64 v[10:11], s[4:5], 0, v[10:11]
	v_and_b32_e32 v32, 0x70, v20
	v_lshlrev_b64 v[150:151], 12, v[4:5]
	v_lshlrev_b64 v[152:153], 12, v[6:7]
	v_lshl_add_u64 v[12:13], v[10:11], 0, v[154:155]
	v_lshl_add_u64 v[0:1], s[6:7], 0, v[32:33]
	v_lshl_add_u64 v[14:15], v[10:11], 0, v[152:153]
	flat_load_dwordx4 v[130:133], v[12:13]
	flat_load_dwordx4 v[134:137], v[14:15]
	v_lshl_add_u64 v[12:13], v[10:11], 0, v[150:151]
	v_lshl_add_u64 v[10:11], v[10:11], 0, v[148:149]
	v_ashrrev_i32_e32 v145, 3, v18
	flat_load_dwordx4 v[122:125], v[12:13]
	flat_load_dwordx4 v[126:129], v[10:11]
	v_mad_i64_i32 v[10:11], s[6:7], v158, s77, v[0:1]
	v_lshl_add_u64 v[10:11], v[10:11], 0, s[88:89]
	v_mad_i64_i32 v[12:13], s[6:7], v145, s77, v[0:1]
	v_lshl_add_u64 v[12:13], v[12:13], 0, s[88:89]
	flat_load_dwordx4 v[114:117], v[10:11]
	flat_load_dwordx4 v[118:121], v[12:13]
	v_ashrrev_i32_e32 v3, 1, v18
	v_and_b32_e32 v3, 0xffffffe0, v3
	v_add_u32_e32 v159, s21, v3
	v_bfe_u32 v3, v17, 5, 1
	v_and_b32_e32 v10, 0xe0, v20
	s_movk_i32 s6, 0x90
	v_and_b32_e32 v5, 31, v17
	v_lshlrev_b32_e32 v165, 4, v3
	v_lshlrev_b32_e32 v166, 2, v3
	v_mul_lo_u32 v17, v145, s6
	v_mul_lo_u32 v18, v158, s6
	v_mad_u64_u32 v[2:3], s[6:7], v2, s9, v[10:11]
	v_and_b32_e32 v7, 8, v19
	v_or_b32_e32 v19, v2, v7
	v_mad_u64_u32 v[2:3], s[6:7], v4, s9, v[10:11]
	v_or_b32_e32 v20, v2, v7
	v_mad_u64_u32 v[2:3], s[6:7], v6, s9, v[10:11]
	v_or_b32_e32 v21, v2, v7
	v_mad_u64_u32 v[2:3], s[6:7], v8, s9, v[10:11]
	v_or_b32_e32 v22, v2, v7
	v_mov_b32_e32 v14, v33
	v_mov_b32_e32 v15, v33
	v_or_b32_e32 v163, v159, v5
	v_mul_u32_u24_e32 v168, 0x90, v5
	v_mul_u32_u24_e32 v169, 0x110, v5
	v_lshl_add_u64 v[156:157], v[0:1], 0, s[88:89]
	v_mov_b32_e32 v0, v33
	v_mov_b32_e32 v1, v33
	v_mov_b32_e32 v2, v33
	v_mov_b32_e32 v3, v33
	v_mov_b32_e32 v4, v33
	v_mov_b32_e32 v5, v33
	v_mov_b32_e32 v6, v33
	v_mov_b32_e32 v7, v33
	v_mov_b32_e32 v8, v33
	v_mov_b32_e32 v9, v33
	v_mov_b32_e32 v10, v33
	v_mov_b32_e32 v11, v33
	v_mov_b32_e32 v12, v33
	v_mov_b32_e32 v13, v33
	v_add_u32_e32 v170, v32, v17
	v_add_u32_e32 v171, v32, v18
	v_lshlrev_b32_e32 v32, 1, v16
	v_add_u32_e32 v172, 0x4800, v19
	v_add_u32_e32 v173, 0x4800, v20
	v_add_u32_e32 v174, 0x4800, v21
	v_add_u32_e32 v175, 0x4800, v22
	v_mov_b64_e32 v[30:31], v[14:15]
	v_mov_b64_e32 v[48:49], v[14:15]
	v_mov_b64_e32 v[64:65], v[14:15]
	v_or_b32_e32 v164, 31, v159
	s_mov_b32 s9, 0
	v_mov_b64_e32 v[28:29], v[12:13]
	v_mov_b64_e32 v[26:27], v[10:11]
	v_mov_b64_e32 v[24:25], v[8:9]
	v_mov_b64_e32 v[22:23], v[6:7]
	v_mov_b64_e32 v[20:21], v[4:5]
	v_mov_b64_e32 v[18:19], v[2:3]
	v_mov_b64_e32 v[16:17], v[0:1]
	v_mov_b64_e32 v[46:47], v[12:13]
	v_mov_b64_e32 v[44:45], v[10:11]
	v_mov_b64_e32 v[42:43], v[8:9]
	v_mov_b64_e32 v[40:41], v[6:7]
	v_mov_b64_e32 v[38:39], v[4:5]
	v_mov_b64_e32 v[36:37], v[2:3]
	v_mov_b64_e32 v[34:35], v[0:1]
	v_mov_b64_e32 v[62:63], v[12:13]
	v_mov_b64_e32 v[60:61], v[10:11]
	v_mov_b64_e32 v[58:59], v[8:9]
	v_mov_b64_e32 v[56:57], v[6:7]
	v_mov_b64_e32 v[54:55], v[4:5]
	v_mov_b64_e32 v[52:53], v[2:3]
	v_mov_b64_e32 v[50:51], v[0:1]
	s_branch .LBB0_306
